# P4 out-projection residual epilogue: the 16 load/fma/store groups no longer wait for each load separately (all loads requested first, same math)
# speedup vs baseline: 1.0231x; 1.0035x over previous
; DI void outproj_tile(const Params& p, int l, int mt, int nt, char* lds, int khalf) {
;     ...
;       const int tok = m0 + wm * 64 + mi * 32 + r;
;       float* rp = p.R + (size_t)tok * DM + nt * 128 + wn * 64 + ni * 32;
; #pragma unroll
;       for (int g = 0; g < 4; ++g) {
;         f32x4 v = *(const f32x4*)(rp + 8 * g + 4 * h);
; #pragma unroll
;         for (int e = 0; e < 4; ++e) v[e] = ALPHA * v[e] + a[4 * g + e];
;         *(f32x4*)(rp + 8 * g + 4 * h) = v;
;       }
; __global__ void __launch_bounds__(NTHREADS) mega(Params p) {
;     ...
;     for (int j = blockIdx.x; j < 512; j += gridDim.x) {
;       const int x = j & 7, a = j >> 3;
;       outproj_tile(p, l, 2 * (a >> 1) + (x >> 2), 2 * (x & 3) + (a & 1), lds, -1);
;     }
.LBB0_2483:
	v_and_b32_e32 v2, 0xdf, v124
	v_or_b32_e32 v72, s0, v2
	v_ashrrev_i32_e32 v73, 31, v72
	v_ashrrev_i32_e32 v2, 2, v124
	v_lshlrev_b64 v[68:69], 12, v[72:73]
	v_readlane_b32 s26, v240, 15
	v_readlane_b32 s27, v240, 16
	v_and_b32_e32 v70, 0xffffffc0, v2
	s_lshl_b32 s60, s10, 9
	v_lshl_add_u64 v[68:69], s[26:27], 0, v[68:69]
	v_ashrrev_i32_e32 v71, 31, v70
	v_lshl_add_u64 v[68:69], v[68:69], 0, s[60:61]
	v_lshlrev_b64 v[74:75], 2, v[70:71]
	v_lshrrev_b32_e32 v2, 1, v124
	v_lshl_add_u64 v[68:69], v[68:69], 0, v[74:75]
	v_and_b32_e32 v2, 16, v2
	v_lshl_add_u64 v[76:77], v[68:69], 0, v[2:3]
	v_or_b32_e32 v80, 32, v72
	v_ashrrev_i32_e32 v81, 31, v80
	v_lshlrev_b64 v[80:81], 12, v[80:81]
	v_lshl_add_u64 v[80:81], s[26:27], 0, v[80:81]
	v_lshl_add_u64 v[80:81], v[80:81], 0, s[60:61]
	v_lshl_add_u64 v[80:81], v[80:81], 0, v[74:75]
	v_lshl_add_u64 v[78:79], v[80:81], 0, v[2:3]
	global_load_dwordx4 v[84:87], v[76:77], off
	global_load_dwordx4 v[88:91], v[76:77], off offset:32
	global_load_dwordx4 v[92:95], v[76:77], off offset:64
	global_load_dwordx4 v[96:99], v[76:77], off offset:96
	global_load_dwordx4 v[100:103], v[76:77], off offset:128
	global_load_dwordx4 v[104:107], v[76:77], off offset:160
	global_load_dwordx4 v[108:111], v[76:77], off offset:192
	global_load_dwordx4 v[112:115], v[76:77], off offset:224
	global_load_dwordx4 v[116:119], v[78:79], off
	global_load_dwordx4 v[120:123], v[78:79], off offset:32
	global_load_dwordx4 v[128:131], v[78:79], off offset:64
	global_load_dwordx4 v[132:135], v[78:79], off offset:96
	global_load_dwordx4 v[136:139], v[78:79], off offset:128
	global_load_dwordx4 v[140:143], v[78:79], off offset:160
	global_load_dwordx4 v[144:147], v[78:79], off offset:192
	global_load_dwordx4 v[148:151], v[78:79], off offset:224
	s_mov_b32 s0, 0x3fd744fd
	v_readlane_b32 s12, v241, 40
	v_readlane_b32 s18, v241, 46
	s_add_i32 s9, s9, s18
	v_readlane_b32 s20, v240, 9
	v_readlane_b32 s22, v240, 11
	v_readlane_b32 s23, v240, 12
	v_readlane_b32 s13, v241, 41
	v_readlane_b32 s17, v241, 45
	s_waitcnt vmcnt(15)
	v_pk_fma_f32 v[52:53], v[84:85], s[0:1], v[52:53] op_sel_hi:[1,0,1]
	v_pk_fma_f32 v[54:55], v[86:87], s[0:1], v[54:55] op_sel_hi:[1,0,1]
	global_store_dwordx4 v[76:77], v[52:55], off
	s_waitcnt vmcnt(15)
	v_pk_fma_f32 v[56:57], v[88:89], s[0:1], v[56:57] op_sel_hi:[1,0,1]
	v_pk_fma_f32 v[58:59], v[90:91], s[0:1], v[58:59] op_sel_hi:[1,0,1]
	global_store_dwordx4 v[76:77], v[56:59], off offset:32
	s_waitcnt vmcnt(15)
	v_pk_fma_f32 v[60:61], v[92:93], s[0:1], v[60:61] op_sel_hi:[1,0,1]
	v_pk_fma_f32 v[62:63], v[94:95], s[0:1], v[62:63] op_sel_hi:[1,0,1]
	global_store_dwordx4 v[76:77], v[60:63], off offset:64
	s_waitcnt vmcnt(15)
	v_pk_fma_f32 v[64:65], v[96:97], s[0:1], v[64:65] op_sel_hi:[1,0,1]
	v_pk_fma_f32 v[66:67], v[98:99], s[0:1], v[66:67] op_sel_hi:[1,0,1]
	global_store_dwordx4 v[76:77], v[64:67], off offset:96
	s_waitcnt vmcnt(15)
	v_pk_fma_f32 v[36:37], v[100:101], s[0:1], v[36:37] op_sel_hi:[1,0,1]
	v_pk_fma_f32 v[38:39], v[102:103], s[0:1], v[38:39] op_sel_hi:[1,0,1]
	global_store_dwordx4 v[76:77], v[36:39], off offset:128
	s_waitcnt vmcnt(15)
	v_pk_fma_f32 v[40:41], v[104:105], s[0:1], v[40:41] op_sel_hi:[1,0,1]
	v_pk_fma_f32 v[42:43], v[106:107], s[0:1], v[42:43] op_sel_hi:[1,0,1]
	global_store_dwordx4 v[76:77], v[40:43], off offset:160
	s_waitcnt vmcnt(15)
	v_pk_fma_f32 v[44:45], v[108:109], s[0:1], v[44:45] op_sel_hi:[1,0,1]
	v_pk_fma_f32 v[46:47], v[110:111], s[0:1], v[46:47] op_sel_hi:[1,0,1]
	global_store_dwordx4 v[76:77], v[44:47], off offset:192
	s_waitcnt vmcnt(15)
	v_pk_fma_f32 v[48:49], v[112:113], s[0:1], v[48:49] op_sel_hi:[1,0,1]
	v_pk_fma_f32 v[50:51], v[114:115], s[0:1], v[50:51] op_sel_hi:[1,0,1]
	global_store_dwordx4 v[76:77], v[48:51], off offset:224
	s_waitcnt vmcnt(15)
	v_pk_fma_f32 v[20:21], v[116:117], s[0:1], v[20:21] op_sel_hi:[1,0,1]
	v_pk_fma_f32 v[22:23], v[118:119], s[0:1], v[22:23] op_sel_hi:[1,0,1]
	global_store_dwordx4 v[78:79], v[20:23], off
	s_waitcnt vmcnt(15)
	v_pk_fma_f32 v[24:25], v[120:121], s[0:1], v[24:25] op_sel_hi:[1,0,1]
	v_pk_fma_f32 v[26:27], v[122:123], s[0:1], v[26:27] op_sel_hi:[1,0,1]
	global_store_dwordx4 v[78:79], v[24:27], off offset:32
	s_waitcnt vmcnt(15)
	v_pk_fma_f32 v[28:29], v[128:129], s[0:1], v[28:29] op_sel_hi:[1,0,1]
	v_pk_fma_f32 v[30:31], v[130:131], s[0:1], v[30:31] op_sel_hi:[1,0,1]
	global_store_dwordx4 v[78:79], v[28:31], off offset:64
	s_waitcnt vmcnt(15)
	v_pk_fma_f32 v[32:33], v[132:133], s[0:1], v[32:33] op_sel_hi:[1,0,1]
	v_pk_fma_f32 v[34:35], v[134:135], s[0:1], v[34:35] op_sel_hi:[1,0,1]
	global_store_dwordx4 v[78:79], v[32:35], off offset:96
	s_waitcnt vmcnt(15)
	v_pk_fma_f32 v[4:5], v[136:137], s[0:1], v[4:5] op_sel_hi:[1,0,1]
	v_pk_fma_f32 v[6:7], v[138:139], s[0:1], v[6:7] op_sel_hi:[1,0,1]
	global_store_dwordx4 v[78:79], v[4:7], off offset:128
	s_waitcnt vmcnt(15)
	v_pk_fma_f32 v[8:9], v[140:141], s[0:1], v[8:9] op_sel_hi:[1,0,1]
	v_pk_fma_f32 v[10:11], v[142:143], s[0:1], v[10:11] op_sel_hi:[1,0,1]
	global_store_dwordx4 v[78:79], v[8:11], off offset:160
	s_waitcnt vmcnt(15)
	v_pk_fma_f32 v[12:13], v[144:145], s[0:1], v[12:13] op_sel_hi:[1,0,1]
	v_pk_fma_f32 v[14:15], v[146:147], s[0:1], v[14:15] op_sel_hi:[1,0,1]
	global_store_dwordx4 v[78:79], v[12:15], off offset:192
	s_waitcnt vmcnt(15)
	v_pk_fma_f32 v[16:17], v[148:149], s[0:1], v[16:17] op_sel_hi:[1,0,1]
	v_pk_fma_f32 v[18:19], v[150:151], s[0:1], v[18:19] op_sel_hi:[1,0,1]
	global_store_dwordx4 v[78:79], v[16:19], off offset:224
	v_readlane_b32 s0, v238, 18
	s_add_i32 s8, s8, s0
	s_cmpk_gt_i32 s9, 0x1ff
	s_cbranch_scc1 .LBB0_2492

; template <bool SWAP, class Epi>
; DI void gemm_tile(const u16* __restrict__ A, int lda, const u16* __restrict__ Bw, int ldb, int K, char* lds, Epi epi) {
;     ...
;   const int lrow = tid >> 3, lkc = tid & 7;
;   u32x4 ra0[4], rb0[2], ra1[4], rb1[2];
;   const u16* ap = A + (size_t)lrow * lda + lkc * 8;
;   const u16* bp = Bw + (size_t)lrow * ldb + lkc * 8;
;   const int nk = K >> 6;
;   auto gload = [&](int kt, u32x4* ra, u32x4* rb) {
; #pragma unroll
;     for (int j = 0; j < 4; ++j) ra[j] = *(const u32x4*)(ap + (size_t)(64 * j) * lda + kt * 64);
; #pragma unroll
;     for (int j = 0; j < 2; ++j) rb[j] = *(const u32x4*)(bp + (size_t)(64 * j) * ldb + kt * 64);
;   };
;   auto lstore = [&](int st, const u32x4* ra, const u32x4* rb) {
;     char* base = lds + st * GEMM_STAGE;
; #pragma unroll
;     for (int j = 0; j < 4; ++j) *(u32x4*)(base + ((lrow + 64 * j) * 72 + lkc * 8) * 2) = ra[j];
; #pragma unroll
;     for (int j = 0; j < 2; ++j) *(u32x4*)(base + 36864 + ((lrow + 64 * j) * 72 + lkc * 8) * 2) = rb[j];
;   };
;   auto compute = [&](int st) {
;     const char* as = lds + st * GEMM_STAGE;
;     const char* bs = as + 36864;
; #pragma unroll
;     for (int ks = 0; ks < 4; ++ks) {
;       bf16x8 af[2], bfr[2];
; #pragma unroll
;       for (int mi = 0; mi < 2; ++mi) af[mi] = *(const bf16x8*)(as + ((wm * 64 + mi * 32 + r) * 72 + ks * 16 + 8 * h) * 2);
; #pragma unroll
;       for (int ni = 0; ni < 2; ++ni) bfr[ni] = *(const bf16x8*)(bs + ((wn * 64 + ni * 32 + r) * 72 + ks * 16 + 8 * h) * 2);
; #pragma unroll
;       for (int mi = 0; mi < 2; ++mi)
; #pragma unroll
;         for (int ni = 0; ni < 2; ++ni) {
;           if (SWAP) acc[mi][ni] = MFMA32(bfr[ni], af[mi], acc[mi][ni]);
;           else acc[mi][ni] = MFMA32(af[mi], bfr[ni], acc[mi][ni]);
;         }
;     }
;   };
;   gload(0, ra0, rb0);
;   lstore(0, ra0, rb0);
;   gload(1, ra1, rb1);
;   __syncthreads();
;   for (int kt = 0; kt < nk; kt += 2) {
;     if (kt + 2 < nk) gload(kt + 2, ra0, rb0);
;     compute(0);
;     lstore(1, ra1, rb1);
;     __syncthreads();
;     if (kt + 3 < nk) gload(kt + 3, ra1, rb1);
;     compute(1);
;     if (kt + 2 < nk) lstore(0, ra0, rb0);
; DI void outproj_tile(const Params& p, int l, int mt, int nt, char* lds, int khalf) {
;     ...
;   const int koff = khalf > 0 ? 512 * khalf : 0, klen = khalf < 0 ? 2048 : 512;
;   const u16* A = p.Mix + (size_t)m0 * 2048 + koff;
.LBB0_2751:
	s_andn2_b64 vcc, exec, s[2:3]
	s_cbranch_vccnz .LBB0_2753
	v_mov_b32_e32 v30, v152
	v_readlane_b32 s2, v239, 26
	v_ashrrev_i32_e32 v28, 3, v30
	v_ashrrev_i32_e32 v29, 31, v28
	s_waitcnt vmcnt(3)
	v_lshlrev_b64 v[4:5], 12, v[28:29]
	v_readlane_b32 s3, v239, 27
	v_lshlrev_b32_e32 v1, 4, v30
	v_and_b32_e32 v2, 0x70, v1
	v_lshl_add_u64 v[6:7], s[2:3], 0, v[4:5]
	v_lshl_add_u64 v[124:125], v[6:7], 0, v[2:3]
	v_add_co_u32_e32 v126, vcc, 0x40000, v124
	v_lshl_add_u64 v[4:5], s[0:1], 0, v[4:5]
	s_nop 0
	v_addc_co_u32_e32 v127, vcc, 0, v125, vcc
	v_add_co_u32_e32 v128, vcc, 0x80000, v124
	v_lshl_add_u64 v[122:123], v[4:5], 0, v[2:3]
	s_nop 0
	v_addc_co_u32_e32 v129, vcc, 0, v125, vcc
	v_add_co_u32_e32 v130, vcc, 0xc0000, v124
	s_mov_b32 s0, 0x40000
	s_nop 0
	v_addc_co_u32_e32 v131, vcc, 0, v125, vcc
	global_load_dwordx4 v[4:7], v[124:125], off
	global_load_dwordx4 v[8:11], v[126:127], off
	global_load_dwordx4 v[12:15], v[128:129], off
	global_load_dwordx4 v[16:19], v[130:131], off
	global_load_dwordx4 v[20:23], v[122:123], off
	v_add_co_u32_e32 v132, vcc, s0, v122
	v_mad_u64_u32 v[28:29], s[0:1], v28, s57, v[2:3]
	s_nop 0
	v_addc_co_u32_e32 v133, vcc, 0, v123, vcc
	global_load_dwordx4 v[24:27], v[132:133], off
	v_add_u32_e32 v2, 0, v28
	v_readlane_b32 s0, v238, 25
	v_and_b32_e32 v1, 0xdf, v30
	v_add_u32_e32 v147, s59, v28
	v_add_u32_e32 v121, s0, v28
	s_mov_b32 s0, 0xfffffc0
	s_mov_b32 s16, 0x3fd744fd
	s_waitcnt vmcnt(5)
	ds_write_b128 v2, v[4:7]
	s_waitcnt vmcnt(4)
	ds_write_b128 v2, v[8:11] offset:9216
	s_waitcnt vmcnt(3)
	ds_write_b128 v2, v[12:15] offset:18432
	s_waitcnt vmcnt(2)
	ds_write_b128 v2, v[16:19] offset:27648
	s_waitcnt vmcnt(1)
	ds_write_b128 v2, v[20:23] offset:36864
	s_waitcnt vmcnt(0)
	ds_write_b128 v2, v[24:27] offset:46080
	global_load_dwordx4 v[92:95], v[124:125], off offset:128
	global_load_dwordx4 v[96:99], v[126:127], off offset:128
	global_load_dwordx4 v[100:103], v[128:129], off offset:128
	global_load_dwordx4 v[104:107], v[130:131], off offset:128
	global_load_dwordx4 v[108:111], v[122:123], off offset:128
	global_load_dwordx4 v[112:115], v[132:133], off offset:128
	s_waitcnt lgkmcnt(0)
	s_barrier
	global_load_dwordx4 v[68:71], v[124:125], off offset:256
	global_load_dwordx4 v[72:75], v[126:127], off offset:256
	global_load_dwordx4 v[76:79], v[128:129], off offset:256
	global_load_dwordx4 v[80:83], v[130:131], off offset:256
	global_load_dwordx4 v[84:87], v[122:123], off offset:256
	global_load_dwordx4 v[88:91], v[132:133], off offset:256
	v_and_b32_e32 v4, 31, v30
	v_lshrrev_b32_e32 v5, 1, v30
	v_lshrrev_b32_e32 v7, 2, v30
	v_and_b32_e32 v5, 16, v5
	v_and_or_b32 v4, v7, s0, v4
	v_mul_u32_u24_e32 v6, 0x90, v1
	v_mul_lo_u32 v4, v4, s57
	v_or_b32_e32 v9, 32, v5
	v_or_b32_e32 v11, 64, v5
	v_or_b32_e32 v13, 0x60, v5
	v_add3_u32 v1, v6, v5, 0
	v_add_u32_e32 v7, v4, v5
	v_add_u32_e32 v8, 0x1200, v4
	v_add_u32_e32 v10, v4, v9
	v_add_u32_e32 v12, v4, v11
	v_add_u32_e32 v4, v4, v13
	v_add_u32_e32 v148, 0, v7
	v_add3_u32 v142, v6, v9, 0
	v_add_u32_e32 v151, 0, v10
	v_add3_u32 v141, v6, v11, 0
	v_add_u32_e32 v150, 0, v12
	v_add3_u32 v136, v6, v13, 0
	v_add_u32_e32 v149, 0, v4
	v_add_u32_e32 v145, s59, v7
	v_add3_u32 v146, v8, v5, s59
	v_add_u32_e32 v143, s59, v10
	v_add3_u32 v144, v8, v9, s59
	v_add_u32_e32 v139, s59, v12
	v_add3_u32 v140, v8, v11, s59
	v_add_u32_e32 v137, s59, v4
	v_add3_u32 v138, v8, v13, s59
	ds_read_b128 v[4:7], v1 offset:4608
	ds_read_b128 v[8:11], v148 offset:41472
	ds_read_b128 v[12:15], v1
	ds_read_b128 v[116:119], v1 offset:32
	ds_read_b128 v[16:19], v148 offset:36864
	ds_read_b128 v[158:161], v148 offset:36896
	s_waitcnt lgkmcnt(1)
	v_mfma_f32_32x32x16_bf16 v[52:67], v[16:19], v[12:15], 0
	ds_read_b128 v[162:165], v142 offset:4608
	ds_read_b128 v[166:169], v151 offset:41472
	v_readlane_b32 s0, v239, 25
	v_mfma_f32_32x32x16_bf16 v[36:51], v[8:11], v[12:15], 0
	v_mfma_f32_32x32x16_bf16 v[20:35], v[16:19], v[4:7], 0
	v_mfma_f32_32x32x16_bf16 v[4:19], v[8:11], v[4:7], 0
	s_waitcnt lgkmcnt(2)
	v_mfma_f32_32x32x16_bf16 v[52:67], v[158:161], v[116:119], v[52:67]
	s_waitcnt lgkmcnt(0)
	v_mfma_f32_32x32x16_bf16 v[36:51], v[166:169], v[116:119], v[36:51]
	v_mfma_f32_32x32x16_bf16 v[20:35], v[158:161], v[162:165], v[20:35]
	v_mfma_f32_32x32x16_bf16 v[4:19], v[166:169], v[162:165], v[4:19]
	ds_read_b128 v[116:119], v1 offset:64
	ds_read_b128 v[158:161], v141 offset:4608
	ds_read_b128 v[162:165], v148 offset:36928
	ds_read_b128 v[166:169], v150 offset:41472
	s_waitcnt lgkmcnt(1)
	v_mfma_f32_32x32x16_bf16 v[52:67], v[162:165], v[116:119], v[52:67]
	s_waitcnt lgkmcnt(0)
	v_mfma_f32_32x32x16_bf16 v[36:51], v[166:169], v[116:119], v[36:51]
	v_mfma_f32_32x32x16_bf16 v[20:35], v[162:165], v[158:161], v[20:35]
	v_mfma_f32_32x32x16_bf16 v[4:19], v[166:169], v[158:161], v[4:19]
	ds_read_b128 v[158:161], v1 offset:96
	ds_read_b128 v[116:119], v136 offset:4608
	ds_read_b128 v[162:165], v148 offset:36960
	ds_read_b128 v[166:169], v149 offset:41472
	s_waitcnt vmcnt(11)
	ds_write_b128 v2, v[92:95] offset:55296
	s_waitcnt vmcnt(10)
	ds_write_b128 v2, v[96:99] offset:64512
	s_waitcnt vmcnt(9)
	ds_write_b128 v121, v[100:103] offset:18432
	s_waitcnt vmcnt(8)
	ds_write_b128 v121, v[104:107] offset:27648
	s_waitcnt vmcnt(7)
	ds_write_b128 v147, v[108:111]
	s_waitcnt vmcnt(6)
	ds_write_b128 v147, v[112:115] offset:9216
	s_waitcnt lgkmcnt(0)
	s_barrier
; #define MFMA32(a, b, c) __builtin_amdgcn_mfma_f32_32x32x16_bf16((a), (b), (c), 0, 0, 0)
; template <bool SWAP, class Epi>
; DI void gemm_tile(const u16* __restrict__ A, int lda, const u16* __restrict__ Bw, int ldb, int K, char* lds, Epi epi) {
;     ...
;   auto compute = [&](int st) {
;     const char* as = lds + st * GEMM_STAGE;
;     const char* bs = as + 36864;
; #pragma unroll
;     for (int ks = 0; ks < 4; ++ks) {
;       bf16x8 af[2], bfr[2];
; #pragma unroll
;       for (int mi = 0; mi < 2; ++mi) af[mi] = *(const bf16x8*)(as + ((wm * 64 + mi * 32 + r) * 72 + ks * 16 + 8 * h) * 2);
; #pragma unroll
;       for (int ni = 0; ni < 2; ++ni) bfr[ni] = *(const bf16x8*)(bs + ((wn * 64 + ni * 32 + r) * 72 + ks * 16 + 8 * h) * 2);
; #pragma unroll
;       for (int mi = 0; mi < 2; ++mi)
; #pragma unroll
;         for (int ni = 0; ni < 2; ++ni) {
;           if (SWAP) acc[mi][ni] = MFMA32(bfr[ni], af[mi], acc[mi][ni]);
;           else acc[mi][ni] = MFMA32(af[mi], bfr[ni], acc[mi][ni]);
;         }
;     }
;   };
;   gload(0, ra0, rb0);
;   lstore(0, ra0, rb0);
;   gload(1, ra1, rb1);
;   __syncthreads();
;   for (int kt = 0; kt < nk; kt += 2) {
;     if (kt + 2 < nk) gload(kt + 2, ra0, rb0);
;     compute(0);
;     lstore(1, ra1, rb1);
;     __syncthreads();
;     if (kt + 3 < nk) gload(kt + 3, ra1, rb1);
;     compute(1);
;     if (kt + 2 < nk) lstore(0, ra0, rb0);
;     __syncthreads();
	global_load_dwordx4 v[92:95], v[124:125], off offset:384
	global_load_dwordx4 v[96:99], v[126:127], off offset:384
	global_load_dwordx4 v[100:103], v[128:129], off offset:384
	global_load_dwordx4 v[104:107], v[130:131], off offset:384
	global_load_dwordx4 v[108:111], v[122:123], off offset:384
	global_load_dwordx4 v[112:115], v[132:133], off offset:384
	v_mfma_f32_32x32x16_bf16 v[52:67], v[162:165], v[158:161], v[52:67]
	v_mfma_f32_32x32x16_bf16 v[36:51], v[166:169], v[158:161], v[36:51]
	v_mfma_f32_32x32x16_bf16 v[20:35], v[162:165], v[116:119], v[20:35]
	v_mfma_f32_32x32x16_bf16 v[4:19], v[166:169], v[116:119], v[4:19]
	ds_read_b128 v[116:119], v1 offset:59904
	ds_read_b128 v[158:161], v145
	ds_read_b128 v[162:165], v146
	ds_read_b128 v[166:169], v1 offset:55296
	ds_read_b128 v[170:173], v1 offset:55328
	s_waitcnt lgkmcnt(1)
	v_mfma_f32_32x32x16_bf16 v[52:67], v[158:161], v[166:169], v[52:67]
	v_mfma_f32_32x32x16_bf16 v[36:51], v[162:165], v[166:169], v[36:51]
	v_mfma_f32_32x32x16_bf16 v[20:35], v[158:161], v[116:119], v[20:35]
	v_mfma_f32_32x32x16_bf16 v[4:19], v[162:165], v[116:119], v[4:19]
	ds_read_b128 v[116:119], v142 offset:59904
	ds_read_b128 v[158:161], v143
	ds_read_b128 v[162:165], v144
	s_waitcnt lgkmcnt(1)
	v_mfma_f32_32x32x16_bf16 v[52:67], v[158:161], v[170:173], v[52:67]
	s_waitcnt lgkmcnt(0)
	v_mfma_f32_32x32x16_bf16 v[36:51], v[162:165], v[170:173], v[36:51]
	v_mfma_f32_32x32x16_bf16 v[20:35], v[158:161], v[116:119], v[20:35]
	v_mfma_f32_32x32x16_bf16 v[4:19], v[162:165], v[116:119], v[4:19]
	ds_read_b128 v[116:119], v1 offset:55360
	ds_read_b128 v[158:161], v141 offset:59904
	ds_read_b128 v[162:165], v139
	ds_read_b128 v[166:169], v140
	s_waitcnt lgkmcnt(1)
	v_mfma_f32_32x32x16_bf16 v[52:67], v[162:165], v[116:119], v[52:67]
	s_waitcnt lgkmcnt(0)
	v_mfma_f32_32x32x16_bf16 v[36:51], v[166:169], v[116:119], v[36:51]
	v_mfma_f32_32x32x16_bf16 v[20:35], v[162:165], v[158:161], v[20:35]
	v_mfma_f32_32x32x16_bf16 v[4:19], v[166:169], v[158:161], v[4:19]
	ds_read_b128 v[116:119], v1 offset:55392
	ds_read_b128 v[158:161], v136 offset:59904
	ds_read_b128 v[162:165], v137
	ds_read_b128 v[166:169], v138
	s_waitcnt vmcnt(11)
	ds_write_b128 v2, v[68:71]
	s_waitcnt vmcnt(10)
	ds_write_b128 v2, v[72:75] offset:9216
	s_waitcnt vmcnt(9)
	ds_write_b128 v2, v[76:79] offset:18432
	s_waitcnt vmcnt(8)
	ds_write_b128 v2, v[80:83] offset:27648
	s_waitcnt vmcnt(7)
	ds_write_b128 v2, v[84:87] offset:36864
	s_waitcnt vmcnt(6)
	ds_write_b128 v2, v[88:91] offset:46080
	s_waitcnt lgkmcnt(0)
	s_barrier
	global_load_dwordx4 v[68:71], v[124:125], off offset:512
	global_load_dwordx4 v[72:75], v[126:127], off offset:512
	global_load_dwordx4 v[76:79], v[128:129], off offset:512
	global_load_dwordx4 v[80:83], v[130:131], off offset:512
	global_load_dwordx4 v[84:87], v[122:123], off offset:512
	global_load_dwordx4 v[88:91], v[132:133], off offset:512
	v_mfma_f32_32x32x16_bf16 v[52:67], v[162:165], v[116:119], v[52:67]
	v_mfma_f32_32x32x16_bf16 v[36:51], v[166:169], v[116:119], v[36:51]
	v_mfma_f32_32x32x16_bf16 v[20:35], v[162:165], v[158:161], v[20:35]
	v_mfma_f32_32x32x16_bf16 v[4:19], v[166:169], v[158:161], v[4:19]
	ds_read_b128 v[116:119], v1 offset:4608
	ds_read_b128 v[158:161], v148 offset:41472
	ds_read_b128 v[162:165], v1
	ds_read_b128 v[166:169], v1 offset:32
	ds_read_b128 v[170:173], v148 offset:36864
	ds_read_b128 v[174:177], v148 offset:36896
	s_waitcnt lgkmcnt(1)
	v_mfma_f32_32x32x16_bf16 v[52:67], v[170:173], v[162:165], v[52:67]
	v_mfma_f32_32x32x16_bf16 v[36:51], v[158:161], v[162:165], v[36:51]
	v_mfma_f32_32x32x16_bf16 v[20:35], v[170:173], v[116:119], v[20:35]
	v_mfma_f32_32x32x16_bf16 v[4:19], v[158:161], v[116:119], v[4:19]
	ds_read_b128 v[116:119], v142 offset:4608
	ds_read_b128 v[158:161], v151 offset:41472
	s_waitcnt lgkmcnt(2)
	v_mfma_f32_32x32x16_bf16 v[52:67], v[174:177], v[166:169], v[52:67]
	s_waitcnt lgkmcnt(0)
	v_mfma_f32_32x32x16_bf16 v[36:51], v[158:161], v[166:169], v[36:51]
	v_mfma_f32_32x32x16_bf16 v[20:35], v[174:177], v[116:119], v[20:35]
	v_mfma_f32_32x32x16_bf16 v[4:19], v[158:161], v[116:119], v[4:19]
	ds_read_b128 v[116:119], v1 offset:64
	ds_read_b128 v[158:161], v141 offset:4608
	ds_read_b128 v[162:165], v148 offset:36928
	ds_read_b128 v[166:169], v150 offset:41472
	s_waitcnt lgkmcnt(1)
	v_mfma_f32_32x32x16_bf16 v[52:67], v[162:165], v[116:119], v[52:67]
	s_waitcnt lgkmcnt(0)
	v_mfma_f32_32x32x16_bf16 v[36:51], v[166:169], v[116:119], v[36:51]
	v_mfma_f32_32x32x16_bf16 v[20:35], v[162:165], v[158:161], v[20:35]
	v_mfma_f32_32x32x16_bf16 v[4:19], v[166:169], v[158:161], v[4:19]
	ds_read_b128 v[116:119], v1 offset:96
	ds_read_b128 v[158:161], v136 offset:4608
	ds_read_b128 v[162:165], v148 offset:36960
	ds_read_b128 v[166:169], v149 offset:41472
	s_waitcnt vmcnt(11)
	ds_write_b128 v2, v[92:95] offset:55296
	s_waitcnt vmcnt(10)
	ds_write_b128 v2, v[96:99] offset:64512
	s_waitcnt vmcnt(9)
	ds_write_b128 v121, v[100:103] offset:18432
	s_waitcnt vmcnt(8)
	ds_write_b128 v121, v[104:107] offset:27648
	s_waitcnt vmcnt(7)
	ds_write_b128 v147, v[108:111]
	s_waitcnt vmcnt(6)
	ds_write_b128 v147, v[112:115] offset:9216
	s_waitcnt lgkmcnt(0)
	s_barrier
; #define MFMA32(a, b, c) __builtin_amdgcn_mfma_f32_32x32x16_bf16((a), (b), (c), 0, 0, 0)
; template <bool SWAP, class Epi>
; DI void gemm_tile(const u16* __restrict__ A, int lda, const u16* __restrict__ Bw, int ldb, int K, char* lds, Epi epi) {
;     ...
;   auto compute = [&](int st) {
;     const char* as = lds + st * GEMM_STAGE;
;     const char* bs = as + 36864;
; #pragma unroll
;     for (int ks = 0; ks < 4; ++ks) {
;       bf16x8 af[2], bfr[2];
; #pragma unroll
;       for (int mi = 0; mi < 2; ++mi) af[mi] = *(const bf16x8*)(as + ((wm * 64 + mi * 32 + r) * 72 + ks * 16 + 8 * h) * 2);
; #pragma unroll
;       for (int ni = 0; ni < 2; ++ni) bfr[ni] = *(const bf16x8*)(bs + ((wn * 64 + ni * 32 + r) * 72 + ks * 16 + 8 * h) * 2);
; #pragma unroll
;       for (int mi = 0; mi < 2; ++mi)
; #pragma unroll
;         for (int ni = 0; ni < 2; ++ni) {
;           if (SWAP) acc[mi][ni] = MFMA32(bfr[ni], af[mi], acc[mi][ni]);
;           else acc[mi][ni] = MFMA32(af[mi], bfr[ni], acc[mi][ni]);
;         }
;     }
;   };
;   gload(0, ra0, rb0);
;   lstore(0, ra0, rb0);
;   gload(1, ra1, rb1);
;   __syncthreads();
;   for (int kt = 0; kt < nk; kt += 2) {
;     if (kt + 2 < nk) gload(kt + 2, ra0, rb0);
;     compute(0);
;     lstore(1, ra1, rb1);
;     __syncthreads();
;     if (kt + 3 < nk) gload(kt + 3, ra1, rb1);
;     compute(1);
;     if (kt + 2 < nk) lstore(0, ra0, rb0);
;     __syncthreads();
	global_load_dwordx4 v[92:95], v[124:125], off offset:640
	global_load_dwordx4 v[96:99], v[126:127], off offset:640
	global_load_dwordx4 v[100:103], v[128:129], off offset:640
	global_load_dwordx4 v[104:107], v[130:131], off offset:640
	global_load_dwordx4 v[108:111], v[122:123], off offset:640
	global_load_dwordx4 v[112:115], v[132:133], off offset:640
	v_mfma_f32_32x32x16_bf16 v[52:67], v[162:165], v[116:119], v[52:67]
	v_mfma_f32_32x32x16_bf16 v[36:51], v[166:169], v[116:119], v[36:51]
	v_mfma_f32_32x32x16_bf16 v[20:35], v[162:165], v[158:161], v[20:35]
	v_mfma_f32_32x32x16_bf16 v[4:19], v[166:169], v[158:161], v[4:19]
	ds_read_b128 v[116:119], v1 offset:59904
	ds_read_b128 v[158:161], v145
	ds_read_b128 v[162:165], v146
	ds_read_b128 v[166:169], v1 offset:55296
	ds_read_b128 v[170:173], v1 offset:55328
	s_waitcnt lgkmcnt(1)
	v_mfma_f32_32x32x16_bf16 v[52:67], v[158:161], v[166:169], v[52:67]
	v_mfma_f32_32x32x16_bf16 v[36:51], v[162:165], v[166:169], v[36:51]
	v_mfma_f32_32x32x16_bf16 v[20:35], v[158:161], v[116:119], v[20:35]
	v_mfma_f32_32x32x16_bf16 v[4:19], v[162:165], v[116:119], v[4:19]
	ds_read_b128 v[116:119], v142 offset:59904
	ds_read_b128 v[158:161], v143
	ds_read_b128 v[162:165], v144
	s_waitcnt lgkmcnt(1)
	v_mfma_f32_32x32x16_bf16 v[52:67], v[158:161], v[170:173], v[52:67]
	s_waitcnt lgkmcnt(0)
	v_mfma_f32_32x32x16_bf16 v[36:51], v[162:165], v[170:173], v[36:51]
	v_mfma_f32_32x32x16_bf16 v[20:35], v[158:161], v[116:119], v[20:35]
	v_mfma_f32_32x32x16_bf16 v[4:19], v[162:165], v[116:119], v[4:19]
	ds_read_b128 v[116:119], v1 offset:55360
	ds_read_b128 v[158:161], v141 offset:59904
	ds_read_b128 v[162:165], v139
	ds_read_b128 v[166:169], v140
	s_waitcnt lgkmcnt(1)
	v_mfma_f32_32x32x16_bf16 v[52:67], v[162:165], v[116:119], v[52:67]
	s_waitcnt lgkmcnt(0)
	v_mfma_f32_32x32x16_bf16 v[36:51], v[166:169], v[116:119], v[36:51]
	v_mfma_f32_32x32x16_bf16 v[20:35], v[162:165], v[158:161], v[20:35]
	v_mfma_f32_32x32x16_bf16 v[4:19], v[166:169], v[158:161], v[4:19]
	ds_read_b128 v[116:119], v1 offset:55392
	ds_read_b128 v[158:161], v136 offset:59904
	ds_read_b128 v[162:165], v137
	ds_read_b128 v[166:169], v138
	s_waitcnt vmcnt(11)
	ds_write_b128 v2, v[68:71]
	s_waitcnt vmcnt(10)
	ds_write_b128 v2, v[72:75] offset:9216
	s_waitcnt vmcnt(9)
	ds_write_b128 v2, v[76:79] offset:18432
	s_waitcnt vmcnt(8)
	ds_write_b128 v2, v[80:83] offset:27648
	s_waitcnt vmcnt(7)
	ds_write_b128 v2, v[84:87] offset:36864
	s_waitcnt vmcnt(6)
	ds_write_b128 v2, v[88:91] offset:46080
	s_waitcnt lgkmcnt(0)
	s_barrier
	global_load_dwordx4 v[68:71], v[124:125], off offset:768
	global_load_dwordx4 v[72:75], v[126:127], off offset:768
	global_load_dwordx4 v[76:79], v[128:129], off offset:768
	global_load_dwordx4 v[80:83], v[130:131], off offset:768
	global_load_dwordx4 v[84:87], v[122:123], off offset:768
	global_load_dwordx4 v[88:91], v[132:133], off offset:768
	v_mfma_f32_32x32x16_bf16 v[52:67], v[162:165], v[116:119], v[52:67]
	v_mfma_f32_32x32x16_bf16 v[36:51], v[166:169], v[116:119], v[36:51]
	v_mfma_f32_32x32x16_bf16 v[20:35], v[162:165], v[158:161], v[20:35]
	v_mfma_f32_32x32x16_bf16 v[4:19], v[166:169], v[158:161], v[4:19]
	ds_read_b128 v[116:119], v1 offset:4608
	ds_read_b128 v[158:161], v148 offset:41472
	ds_read_b128 v[162:165], v1
	ds_read_b128 v[166:169], v1 offset:32
	ds_read_b128 v[170:173], v148 offset:36864
	ds_read_b128 v[174:177], v148 offset:36896
	s_waitcnt lgkmcnt(1)
	v_mfma_f32_32x32x16_bf16 v[52:67], v[170:173], v[162:165], v[52:67]
	v_mfma_f32_32x32x16_bf16 v[36:51], v[158:161], v[162:165], v[36:51]
	v_mfma_f32_32x32x16_bf16 v[20:35], v[170:173], v[116:119], v[20:35]
	v_mfma_f32_32x32x16_bf16 v[4:19], v[158:161], v[116:119], v[4:19]
	ds_read_b128 v[116:119], v142 offset:4608
	ds_read_b128 v[158:161], v151 offset:41472
	s_waitcnt lgkmcnt(2)
	v_mfma_f32_32x32x16_bf16 v[52:67], v[174:177], v[166:169], v[52:67]
	s_waitcnt lgkmcnt(0)
	v_mfma_f32_32x32x16_bf16 v[36:51], v[158:161], v[166:169], v[36:51]
	v_mfma_f32_32x32x16_bf16 v[20:35], v[174:177], v[116:119], v[20:35]
	v_mfma_f32_32x32x16_bf16 v[4:19], v[158:161], v[116:119], v[4:19]
	ds_read_b128 v[116:119], v1 offset:64
	ds_read_b128 v[158:161], v141 offset:4608
	ds_read_b128 v[162:165], v148 offset:36928
	ds_read_b128 v[166:169], v150 offset:41472
	s_waitcnt lgkmcnt(1)
	v_mfma_f32_32x32x16_bf16 v[52:67], v[162:165], v[116:119], v[52:67]
	s_waitcnt lgkmcnt(0)
	v_mfma_f32_32x32x16_bf16 v[36:51], v[166:169], v[116:119], v[36:51]
	v_mfma_f32_32x32x16_bf16 v[20:35], v[162:165], v[158:161], v[20:35]
	v_mfma_f32_32x32x16_bf16 v[4:19], v[166:169], v[158:161], v[4:19]
	ds_read_b128 v[116:119], v1 offset:96
	ds_read_b128 v[158:161], v136 offset:4608
	ds_read_b128 v[162:165], v148 offset:36960
	ds_read_b128 v[166:169], v149 offset:41472
	s_waitcnt vmcnt(11)
	ds_write_b128 v2, v[92:95] offset:55296
	s_waitcnt vmcnt(10)
	ds_write_b128 v2, v[96:99] offset:64512
	s_waitcnt vmcnt(9)
	ds_write_b128 v121, v[100:103] offset:18432
	s_waitcnt vmcnt(8)
	ds_write_b128 v121, v[104:107] offset:27648
	s_waitcnt vmcnt(7)
	ds_write_b128 v147, v[108:111]
	s_waitcnt vmcnt(6)
	ds_write_b128 v147, v[112:115] offset:9216
	s_waitcnt lgkmcnt(0)
	s_barrier
; #define MFMA32(a, b, c) __builtin_amdgcn_mfma_f32_32x32x16_bf16((a), (b), (c), 0, 0, 0)
; template <bool SWAP, class Epi>
; DI void gemm_tile(const u16* __restrict__ A, int lda, const u16* __restrict__ Bw, int ldb, int K, char* lds, Epi epi) {
;     ...
;   auto compute = [&](int st) {
;     const char* as = lds + st * GEMM_STAGE;
;     const char* bs = as + 36864;
; #pragma unroll
;     for (int ks = 0; ks < 4; ++ks) {
;       bf16x8 af[2], bfr[2];
; #pragma unroll
;       for (int mi = 0; mi < 2; ++mi) af[mi] = *(const bf16x8*)(as + ((wm * 64 + mi * 32 + r) * 72 + ks * 16 + 8 * h) * 2);
; #pragma unroll
;       for (int ni = 0; ni < 2; ++ni) bfr[ni] = *(const bf16x8*)(bs + ((wn * 64 + ni * 32 + r) * 72 + ks * 16 + 8 * h) * 2);
; #pragma unroll
;       for (int mi = 0; mi < 2; ++mi)
; #pragma unroll
;         for (int ni = 0; ni < 2; ++ni) {
;           if (SWAP) acc[mi][ni] = MFMA32(bfr[ni], af[mi], acc[mi][ni]);
;           else acc[mi][ni] = MFMA32(af[mi], bfr[ni], acc[mi][ni]);
;         }
;     }
;   };
;   gload(0, ra0, rb0);
;   lstore(0, ra0, rb0);
;   gload(1, ra1, rb1);
;   __syncthreads();
;   for (int kt = 0; kt < nk; kt += 2) {
;     if (kt + 2 < nk) gload(kt + 2, ra0, rb0);
;     compute(0);
;     lstore(1, ra1, rb1);
;     __syncthreads();
;     if (kt + 3 < nk) gload(kt + 3, ra1, rb1);
;     compute(1);
;     if (kt + 2 < nk) lstore(0, ra0, rb0);
;     __syncthreads();
	global_load_dwordx4 v[92:95], v[124:125], off offset:896
	global_load_dwordx4 v[96:99], v[126:127], off offset:896
	global_load_dwordx4 v[100:103], v[128:129], off offset:896
	global_load_dwordx4 v[104:107], v[130:131], off offset:896
	global_load_dwordx4 v[108:111], v[122:123], off offset:896
	global_load_dwordx4 v[112:115], v[132:133], off offset:896
	v_mfma_f32_32x32x16_bf16 v[52:67], v[162:165], v[116:119], v[52:67]
	v_mfma_f32_32x32x16_bf16 v[36:51], v[166:169], v[116:119], v[36:51]
	v_mfma_f32_32x32x16_bf16 v[20:35], v[162:165], v[158:161], v[20:35]
	v_mfma_f32_32x32x16_bf16 v[4:19], v[166:169], v[158:161], v[4:19]
	ds_read_b128 v[116:119], v1 offset:59904
	ds_read_b128 v[122:125], v145
	ds_read_b128 v[126:129], v146
	ds_read_b128 v[130:133], v1 offset:55296
	ds_read_b128 v[158:161], v1 offset:55328
	s_waitcnt lgkmcnt(1)
	v_mfma_f32_32x32x16_bf16 v[52:67], v[122:125], v[130:133], v[52:67]
	v_mfma_f32_32x32x16_bf16 v[36:51], v[126:129], v[130:133], v[36:51]
	v_mfma_f32_32x32x16_bf16 v[20:35], v[122:125], v[116:119], v[20:35]
	v_mfma_f32_32x32x16_bf16 v[4:19], v[126:129], v[116:119], v[4:19]
	ds_read_b128 v[116:119], v142 offset:59904
	ds_read_b128 v[122:125], v143
	ds_read_b128 v[126:129], v144
	s_waitcnt lgkmcnt(1)
	v_mfma_f32_32x32x16_bf16 v[52:67], v[122:125], v[158:161], v[52:67]
	s_waitcnt lgkmcnt(0)
	v_mfma_f32_32x32x16_bf16 v[36:51], v[126:129], v[158:161], v[36:51]
	v_mfma_f32_32x32x16_bf16 v[20:35], v[122:125], v[116:119], v[20:35]
	v_mfma_f32_32x32x16_bf16 v[4:19], v[126:129], v[116:119], v[4:19]
	ds_read_b128 v[116:119], v1 offset:55360
	ds_read_b128 v[122:125], v141 offset:59904
	ds_read_b128 v[126:129], v139
	ds_read_b128 v[130:133], v140
	s_waitcnt lgkmcnt(1)
	v_mfma_f32_32x32x16_bf16 v[52:67], v[126:129], v[116:119], v[52:67]
	s_waitcnt lgkmcnt(0)
	v_mfma_f32_32x32x16_bf16 v[36:51], v[130:133], v[116:119], v[36:51]
	v_mfma_f32_32x32x16_bf16 v[20:35], v[126:129], v[122:125], v[20:35]
	v_mfma_f32_32x32x16_bf16 v[4:19], v[130:133], v[122:125], v[4:19]
	ds_read_b128 v[116:119], v1 offset:55392
	ds_read_b128 v[122:125], v136 offset:59904
	ds_read_b128 v[126:129], v137
	ds_read_b128 v[130:133], v138
	s_waitcnt vmcnt(11)
	ds_write_b128 v2, v[68:71]
	s_waitcnt vmcnt(10)
	ds_write_b128 v2, v[72:75] offset:9216
	s_waitcnt vmcnt(9)
	ds_write_b128 v2, v[76:79] offset:18432
	s_waitcnt vmcnt(8)
	ds_write_b128 v2, v[80:83] offset:27648
	s_waitcnt vmcnt(7)
	ds_write_b128 v2, v[84:87] offset:36864
	s_waitcnt vmcnt(6)
	ds_write_b128 v2, v[88:91] offset:46080
	s_waitcnt lgkmcnt(0)
	s_barrier
	ds_read_b128 v[68:71], v1 offset:4608
	ds_read_b128 v[72:75], v148 offset:41472
	ds_read_b128 v[76:79], v1
	ds_read_b128 v[80:83], v1 offset:32
	ds_read_b128 v[84:87], v148 offset:36864
	ds_read_b128 v[88:91], v148 offset:36896
	v_mfma_f32_32x32x16_bf16 v[52:67], v[126:129], v[116:119], v[52:67]
	v_mfma_f32_32x32x16_bf16 v[36:51], v[130:133], v[116:119], v[36:51]
	v_mfma_f32_32x32x16_bf16 v[20:35], v[126:129], v[122:125], v[20:35]
	v_mfma_f32_32x32x16_bf16 v[4:19], v[130:133], v[122:125], v[4:19]
	s_waitcnt lgkmcnt(1)
	v_mfma_f32_32x32x16_bf16 v[52:67], v[84:87], v[76:79], v[52:67]
	v_mfma_f32_32x32x16_bf16 v[36:51], v[72:75], v[76:79], v[36:51]
	v_mfma_f32_32x32x16_bf16 v[20:35], v[84:87], v[68:71], v[20:35]
	v_mfma_f32_32x32x16_bf16 v[4:19], v[72:75], v[68:71], v[4:19]
	ds_read_b128 v[68:71], v142 offset:4608
	ds_read_b128 v[72:75], v151 offset:41472
	s_waitcnt lgkmcnt(2)
	v_mfma_f32_32x32x16_bf16 v[52:67], v[88:91], v[80:83], v[52:67]
	s_waitcnt lgkmcnt(0)
	v_mfma_f32_32x32x16_bf16 v[36:51], v[72:75], v[80:83], v[36:51]
	v_mfma_f32_32x32x16_bf16 v[20:35], v[88:91], v[68:71], v[20:35]
	v_mfma_f32_32x32x16_bf16 v[4:19], v[72:75], v[68:71], v[4:19]
	ds_read_b128 v[68:71], v1 offset:64
	ds_read_b128 v[72:75], v141 offset:4608
	ds_read_b128 v[76:79], v148 offset:36928
	ds_read_b128 v[80:83], v150 offset:41472
	s_waitcnt lgkmcnt(1)
	v_mfma_f32_32x32x16_bf16 v[52:67], v[76:79], v[68:71], v[52:67]
	s_waitcnt lgkmcnt(0)
	v_mfma_f32_32x32x16_bf16 v[36:51], v[80:83], v[68:71], v[36:51]
	v_mfma_f32_32x32x16_bf16 v[20:35], v[76:79], v[72:75], v[20:35]
	v_mfma_f32_32x32x16_bf16 v[4:19], v[80:83], v[72:75], v[4:19]
	ds_read_b128 v[68:71], v1 offset:96
	ds_read_b128 v[72:75], v136 offset:4608
	ds_read_b128 v[76:79], v148 offset:36960
	ds_read_b128 v[80:83], v149 offset:41472
	s_waitcnt vmcnt(5)
	ds_write_b128 v2, v[92:95] offset:55296
	s_waitcnt vmcnt(4)
	ds_write_b128 v2, v[96:99] offset:64512
	s_waitcnt vmcnt(3)
	ds_write_b128 v121, v[100:103] offset:18432
	s_waitcnt vmcnt(2)
	ds_write_b128 v121, v[104:107] offset:27648
	s_waitcnt vmcnt(1)
	ds_write_b128 v147, v[108:111]
	s_waitcnt vmcnt(0)
	ds_write_b128 v147, v[112:115] offset:9216
	s_waitcnt lgkmcnt(0)
	s_barrier
; #define MFMA32(a, b, c) __builtin_amdgcn_mfma_f32_32x32x16_bf16((a), (b), (c), 0, 0, 0)
; template <bool SWAP, class Epi>
; DI void gemm_tile(const u16* __restrict__ A, int lda, const u16* __restrict__ Bw, int ldb, int K, char* lds, Epi epi) {
;     ...
;   auto compute = [&](int st) {
;     const char* as = lds + st * GEMM_STAGE;
;     const char* bs = as + 36864;
; #pragma unroll
;     for (int ks = 0; ks < 4; ++ks) {
;       bf16x8 af[2], bfr[2];
; #pragma unroll
;       for (int mi = 0; mi < 2; ++mi) af[mi] = *(const bf16x8*)(as + ((wm * 64 + mi * 32 + r) * 72 + ks * 16 + 8 * h) * 2);
; #pragma unroll
;       for (int ni = 0; ni < 2; ++ni) bfr[ni] = *(const bf16x8*)(bs + ((wn * 64 + ni * 32 + r) * 72 + ks * 16 + 8 * h) * 2);
; #pragma unroll
;       for (int mi = 0; mi < 2; ++mi)
; #pragma unroll
;         for (int ni = 0; ni < 2; ++ni) {
;           if (SWAP) acc[mi][ni] = MFMA32(bfr[ni], af[mi], acc[mi][ni]);
;           else acc[mi][ni] = MFMA32(af[mi], bfr[ni], acc[mi][ni]);
;         }
;     }
;   };
;   gload(0, ra0, rb0);
;   lstore(0, ra0, rb0);
;   gload(1, ra1, rb1);
;   __syncthreads();
;   for (int kt = 0; kt < nk; kt += 2) {
;     if (kt + 2 < nk) gload(kt + 2, ra0, rb0);
;     compute(0);
;     lstore(1, ra1, rb1);
;     __syncthreads();
;     if (kt + 3 < nk) gload(kt + 3, ra1, rb1);
;     compute(1);
;     if (kt + 2 < nk) lstore(0, ra0, rb0);
;     __syncthreads();
; DI void outproj_tile(const Params& p, int l, int mt, int nt, char* lds, int khalf) {
;     ...
;       const int tok = m0 + wm * 64 + mi * 32 + r;
;       float* rp = p.R + (size_t)tok * DM + nt * 128 + wn * 64 + ni * 32;
	v_ashrrev_i32_e32 v121, 31, v120
	v_mfma_f32_32x32x16_bf16 v[52:67], v[76:79], v[68:71], v[52:67]
	v_mfma_f32_32x32x16_bf16 v[36:51], v[80:83], v[68:71], v[36:51]
	v_mfma_f32_32x32x16_bf16 v[20:35], v[76:79], v[72:75], v[20:35]
	v_mfma_f32_32x32x16_bf16 v[4:19], v[80:83], v[72:75], v[4:19]
	ds_read_b128 v[68:71], v1 offset:59904
	ds_read_b128 v[72:75], v145
	ds_read_b128 v[76:79], v146
	ds_read_b128 v[80:83], v1 offset:55296
	ds_read_b128 v[84:87], v1 offset:55328
	s_waitcnt lgkmcnt(1)
	v_mfma_f32_32x32x16_bf16 v[52:67], v[72:75], v[80:83], v[52:67]
	v_mfma_f32_32x32x16_bf16 v[36:51], v[76:79], v[80:83], v[36:51]
	v_mfma_f32_32x32x16_bf16 v[20:35], v[72:75], v[68:71], v[20:35]
	v_mfma_f32_32x32x16_bf16 v[4:19], v[76:79], v[68:71], v[4:19]
	ds_read_b128 v[68:71], v142 offset:59904
	ds_read_b128 v[72:75], v143
	ds_read_b128 v[76:79], v144
	s_waitcnt lgkmcnt(1)
	v_mfma_f32_32x32x16_bf16 v[52:67], v[72:75], v[84:87], v[52:67]
	s_waitcnt lgkmcnt(0)
	v_mfma_f32_32x32x16_bf16 v[36:51], v[76:79], v[84:87], v[36:51]
	v_mfma_f32_32x32x16_bf16 v[20:35], v[72:75], v[68:71], v[20:35]
	v_mfma_f32_32x32x16_bf16 v[4:19], v[76:79], v[68:71], v[4:19]
	ds_read_b128 v[68:71], v1 offset:55360
	ds_read_b128 v[72:75], v141 offset:59904
	ds_read_b128 v[76:79], v139
	ds_read_b128 v[80:83], v140
	s_waitcnt lgkmcnt(1)
	v_mfma_f32_32x32x16_bf16 v[52:67], v[76:79], v[68:71], v[52:67]
	s_waitcnt lgkmcnt(0)
	v_mfma_f32_32x32x16_bf16 v[36:51], v[80:83], v[68:71], v[36:51]
	v_mfma_f32_32x32x16_bf16 v[20:35], v[76:79], v[72:75], v[20:35]
	v_mfma_f32_32x32x16_bf16 v[4:19], v[80:83], v[72:75], v[4:19]
	ds_read_b128 v[68:71], v1 offset:55392
	ds_read_b128 v[72:75], v136 offset:59904
	ds_read_b128 v[76:79], v137
	ds_read_b128 v[80:83], v138
	v_or3_b32 v1, v135, s0, v134
	v_readlane_b32 s0, v239, 34
	v_lshlrev_b32_e32 v2, 12, v1
	v_readlane_b32 s1, v239, 35
	v_mov_b32_e32 v1, v3
	s_waitcnt lgkmcnt(0)
	v_mfma_f32_32x32x16_bf16 v[52:67], v[76:79], v[68:71], v[52:67]
	s_barrier
; DI void outproj_tile(const Params& p, int l, int mt, int nt, char* lds, int khalf) {
;     ...
;       const int tok = m0 + wm * 64 + mi * 32 + r;
;       float* rp = p.R + (size_t)tok * DM + nt * 128 + wn * 64 + ni * 32;
; #pragma unroll
;       for (int g = 0; g < 4; ++g) {
;         f32x4 v = *(const f32x4*)(rp + 8 * g + 4 * h);
; #pragma unroll
;         for (int e = 0; e < 4; ++e) v[e] = ALPHA * v[e] + a[4 * g + e];
;         *(f32x4*)(rp + 8 * g + 4 * h) = v;
;       }
; __global__ void __launch_bounds__(NTHREADS) mega(Params p) {
;     ...
;     if (blockIdx.x < 64) {
;       const int j = 512 + (blockIdx.x >> 2), x = j & 7, a = j >> 3;
;       outproj_tile(p, l, 2 * (a >> 1) + (x >> 2), 2 * (x & 3) + (a & 1), lds, blockIdx.x & 3);
	v_mfma_f32_32x32x16_bf16 v[36:51], v[80:83], v[68:71], v[36:51]
	v_lshl_add_u64 v[68:69], s[0:1], 0, v[2:3]
	v_readlane_b32 s14, v240, 15
	v_readlane_b32 s15, v240, 16
	v_readlane_b32 s0, v239, 32
	v_readlane_b32 s1, v239, 33
	v_mfma_f32_32x32x16_bf16 v[20:35], v[76:79], v[72:75], v[20:35]
	v_readlane_b32 s3, v240, 4
	v_readlane_b32 s8, v240, 9
	v_mfma_f32_32x32x16_bf16 v[4:19], v[80:83], v[72:75], v[4:19]
	v_lshlrev_b64 v[72:73], 2, v[120:121]
	v_lshl_add_u64 v[68:69], v[68:69], 0, v[72:73]
	v_lshl_add_u64 v[74:75], v[68:69], 0, v[0:1]
	global_load_dwordx4 v[84:87], v[74:75], off
	global_load_dwordx4 v[88:91], v[74:75], off offset:32
	global_load_dwordx4 v[92:95], v[74:75], off offset:64
	global_load_dwordx4 v[96:99], v[74:75], off offset:96
	global_load_dwordx4 v[100:103], v[74:75], off offset:128
	global_load_dwordx4 v[104:107], v[74:75], off offset:160
	global_load_dwordx4 v[108:111], v[74:75], off offset:192
	global_load_dwordx4 v[112:115], v[74:75], off offset:224
	v_lshl_add_u64 v[78:79], s[14:15], 0, v[2:3]
	v_lshl_add_u64 v[78:79], s[0:1], 2, v[78:79]
	v_lshl_add_u64 v[78:79], v[78:79], 0, v[72:73]
	v_lshl_add_u64 v[78:79], v[78:79], 0, v[0:1]
	s_mov_b64 s[0:1], 0x20000
	v_lshl_add_u64 v[76:77], v[78:79], 0, s[0:1]
	global_load_dwordx4 v[120:123], v[76:77], off
	global_load_dwordx4 v[124:127], v[76:77], off offset:32
	global_load_dwordx4 v[128:131], v[76:77], off offset:64
	global_load_dwordx4 v[132:135], v[76:77], off offset:96
	global_load_dwordx4 v[136:139], v[76:77], off offset:128
	global_load_dwordx4 v[140:143], v[76:77], off offset:160
	global_load_dwordx4 v[144:147], v[76:77], off offset:192
	global_load_dwordx4 v[148:151], v[76:77], off offset:224
	v_readlane_b32 s9, v240, 10
	v_readlane_b32 s13, v240, 14
	s_waitcnt vmcnt(15)
	v_pk_fma_f32 v[52:53], v[84:85], s[16:17], v[52:53] op_sel_hi:[1,0,1]
	v_pk_fma_f32 v[54:55], v[86:87], s[16:17], v[54:55] op_sel_hi:[1,0,1]
	global_store_dwordx4 v[74:75], v[52:55], off
	s_waitcnt vmcnt(15)
	v_pk_fma_f32 v[56:57], v[88:89], s[16:17], v[56:57] op_sel_hi:[1,0,1]
	v_pk_fma_f32 v[58:59], v[90:91], s[16:17], v[58:59] op_sel_hi:[1,0,1]
	global_store_dwordx4 v[74:75], v[56:59], off offset:32
	s_waitcnt vmcnt(15)
	v_pk_fma_f32 v[60:61], v[92:93], s[16:17], v[60:61] op_sel_hi:[1,0,1]
	v_pk_fma_f32 v[62:63], v[94:95], s[16:17], v[62:63] op_sel_hi:[1,0,1]
	global_store_dwordx4 v[74:75], v[60:63], off offset:64
	s_waitcnt vmcnt(15)
	v_pk_fma_f32 v[64:65], v[96:97], s[16:17], v[64:65] op_sel_hi:[1,0,1]
	v_pk_fma_f32 v[66:67], v[98:99], s[16:17], v[66:67] op_sel_hi:[1,0,1]
	global_store_dwordx4 v[74:75], v[64:67], off offset:96
	s_waitcnt vmcnt(15)
	v_pk_fma_f32 v[36:37], v[100:101], s[16:17], v[36:37] op_sel_hi:[1,0,1]
	v_pk_fma_f32 v[38:39], v[102:103], s[16:17], v[38:39] op_sel_hi:[1,0,1]
	global_store_dwordx4 v[74:75], v[36:39], off offset:128
	s_waitcnt vmcnt(15)
	v_pk_fma_f32 v[40:41], v[104:105], s[16:17], v[40:41] op_sel_hi:[1,0,1]
	v_pk_fma_f32 v[42:43], v[106:107], s[16:17], v[42:43] op_sel_hi:[1,0,1]
	global_store_dwordx4 v[74:75], v[40:43], off offset:160
	s_waitcnt vmcnt(15)
	v_pk_fma_f32 v[44:45], v[108:109], s[16:17], v[44:45] op_sel_hi:[1,0,1]
	v_pk_fma_f32 v[46:47], v[110:111], s[16:17], v[46:47] op_sel_hi:[1,0,1]
	global_store_dwordx4 v[74:75], v[44:47], off offset:192
	s_waitcnt vmcnt(15)
	v_pk_fma_f32 v[48:49], v[112:113], s[16:17], v[48:49] op_sel_hi:[1,0,1]
	v_pk_fma_f32 v[50:51], v[114:115], s[16:17], v[50:51] op_sel_hi:[1,0,1]
	global_store_dwordx4 v[74:75], v[48:51], off offset:224
	s_waitcnt vmcnt(15)
	v_pk_fma_f32 v[20:21], v[120:121], s[16:17], v[20:21] op_sel_hi:[1,0,1]
	v_pk_fma_f32 v[22:23], v[122:123], s[16:17], v[22:23] op_sel_hi:[1,0,1]
	global_store_dwordx4 v[76:77], v[20:23], off
	s_waitcnt vmcnt(15)
	v_pk_fma_f32 v[24:25], v[124:125], s[16:17], v[24:25] op_sel_hi:[1,0,1]
	v_pk_fma_f32 v[26:27], v[126:127], s[16:17], v[26:27] op_sel_hi:[1,0,1]
	global_store_dwordx4 v[76:77], v[24:27], off offset:32
	s_waitcnt vmcnt(15)
	v_pk_fma_f32 v[28:29], v[128:129], s[16:17], v[28:29] op_sel_hi:[1,0,1]
	v_pk_fma_f32 v[30:31], v[130:131], s[16:17], v[30:31] op_sel_hi:[1,0,1]
	global_store_dwordx4 v[76:77], v[28:31], off offset:64
	s_waitcnt vmcnt(15)
	v_pk_fma_f32 v[32:33], v[132:133], s[16:17], v[32:33] op_sel_hi:[1,0,1]
	v_pk_fma_f32 v[34:35], v[134:135], s[16:17], v[34:35] op_sel_hi:[1,0,1]
	global_store_dwordx4 v[76:77], v[32:35], off offset:96
	s_waitcnt vmcnt(15)
	v_pk_fma_f32 v[4:5], v[136:137], s[16:17], v[4:5] op_sel_hi:[1,0,1]
	v_pk_fma_f32 v[6:7], v[138:139], s[16:17], v[6:7] op_sel_hi:[1,0,1]
	global_store_dwordx4 v[76:77], v[4:7], off offset:128
	s_waitcnt vmcnt(15)
	v_pk_fma_f32 v[8:9], v[140:141], s[16:17], v[8:9] op_sel_hi:[1,0,1]
	v_pk_fma_f32 v[10:11], v[142:143], s[16:17], v[10:11] op_sel_hi:[1,0,1]
	global_store_dwordx4 v[76:77], v[8:11], off offset:160
	s_waitcnt vmcnt(15)
	v_pk_fma_f32 v[12:13], v[144:145], s[16:17], v[12:13] op_sel_hi:[1,0,1]
	v_pk_fma_f32 v[14:15], v[146:147], s[16:17], v[14:15] op_sel_hi:[1,0,1]
	global_store_dwordx4 v[76:77], v[12:15], off offset:192
	s_waitcnt vmcnt(15)
	v_pk_fma_f32 v[16:17], v[148:149], s[16:17], v[16:17] op_sel_hi:[1,0,1]
	v_pk_fma_f32 v[18:19], v[150:151], s[16:17], v[18:19] op_sel_hi:[1,0,1]
	global_store_dwordx4 v[76:77], v[16:19], off offset:224
